# ln1/router phase: router logits on the f32 matrix cores (v_mfma_f32_16x16x4_f32, 16 rows per batch, weights in registers) and all 8 input rows of a wave loaded up front
# speedup vs baseline: 1.0064x; 1.0064x over previous
; #define LAS __attribute__((address_space(3)))
; __device__ __forceinline__ int fresh_tid() { int t = threadIdx.x; asm volatile("" : "+v"(t)); return t; }
; __device__ void phase_ln1_router(const Params& p, int l, LAS unsigned char* lds) {
;     LAS float* rw_s = (LAS float*)lds;
;     const int tid = fresh_tid(), lane = tid & 63, wv = tid >> 6;
;     const float* rw = p.router_w + (size_t)l * DM * NE;
;     for (int i0 = 0; i0 < DM * NE; i0 += 8 * NTHREADS) { float rr[8];
; #pragma unroll
;         for (int q = 0; q < 8; ++q) rr[q] = rw[i0 + q * NTHREADS + tid];
; #pragma unroll
;         for (int q = 0; q < 8; ++q) { const int i = i0 + q * NTHREADS + tid, d = i >> 4, e = i & 15; rw_s[e * RWP + d] = rr[q]; } }
;     __syncthreads();
;     const bf16_t* XP = (const bf16_t*)(p.ws + WS_XA); bf16_t* XB = (bf16_t*)(p.ws + WS_XB); float* AFF = (float*)(p.ws + WS_AFF);
;     const float* g = p.ln_mix_g + l * DM; const float* b = p.ln_mix_b + l * DM;
;     f32x4 gv[4], bv[4];
; #pragma unroll
;     for (int j = 0; j < 4; ++j) { gv[j] = *(const f32x4*)(g + lane * 4 + 256 * j); bv[j] = *(const f32x4*)(b + lane * 4 + 256 * j); }
;     const int rstride = gridDim.x * 8;
;     u32x2 raw[4];
;     { const int row0 = blockIdx.x * 8 + wv;
;       if (row0 < SEQ) {
; #pragma unroll
;           for (int j = 0; j < 4; ++j) raw[j] = *(const u32x2*)(XP + (size_t)row0 * DM + lane * 4 + 256 * j); } }
.LBB0_310:
	s_andn2_b64 vcc, exec, s[4:5]
	s_cbranch_vccnz .LBB0_319
	s_ashr_i32 s27, s26, 31
	v_readlane_b32 s8, v252, 40
	s_lshl_b64 s[4:5], s[26:27], 16
	v_readlane_b32 s18, v252, 50
	s_waitcnt vmcnt(0)
	v_mov_b32_e32 v38, v213
	v_readlane_b32 s19, v252, 51
	s_add_u32 s4, s18, s4
	s_addc_u32 s5, s19, s5
	v_and_b32_e32 v0, 15, v38
	s_movk_i32 s6, 0x1010
	v_ashrrev_i32_e32 v39, 31, v38
	v_mad_u32_u24 v14, v0, s6, 0
	v_lshl_add_u64 v[0:1], v[38:39], 2, s[4:5]
	v_lshrrev_b32_e32 v172, 6, v38
	v_and_b32_e32 v173, 63, v38
	v_and_b32_e32 v174, 15, v38
	v_bfe_u32 v175, v38, 4, 2
	v_lshlrev_b32_e32 v187, 13, v172
	v_lshl_add_u32 v187, v175, 8, v187
	v_lshl_add_u32 v187, v174, 2, v187
	s_add_u32 s6, s4, 0x1000
	s_addc_u32 s7, s5, 0
	global_load_dword v92, v187, s[4:5]
	global_load_dword v93, v187, s[4:5] offset:64
	global_load_dword v94, v187, s[4:5] offset:128
	global_load_dword v95, v187, s[4:5] offset:192
	global_load_dword v96, v187, s[4:5] offset:1024
	global_load_dword v97, v187, s[4:5] offset:1088
	global_load_dword v98, v187, s[4:5] offset:1152
	global_load_dword v99, v187, s[4:5] offset:1216
	global_load_dword v100, v187, s[4:5] offset:2048
	global_load_dword v101, v187, s[4:5] offset:2112
	global_load_dword v102, v187, s[4:5] offset:2176
	global_load_dword v103, v187, s[4:5] offset:2240
	global_load_dword v104, v187, s[4:5] offset:3072
	global_load_dword v105, v187, s[4:5] offset:3136
	global_load_dword v106, v187, s[4:5] offset:3200
	global_load_dword v107, v187, s[4:5] offset:3264
	global_load_dword v108, v187, s[6:7]
	global_load_dword v109, v187, s[6:7] offset:64
	global_load_dword v110, v187, s[6:7] offset:128
	global_load_dword v111, v187, s[6:7] offset:192
	global_load_dword v112, v187, s[6:7] offset:1024
	global_load_dword v113, v187, s[6:7] offset:1088
	global_load_dword v114, v187, s[6:7] offset:1152
	global_load_dword v115, v187, s[6:7] offset:1216
	global_load_dword v116, v187, s[6:7] offset:2048
	global_load_dword v117, v187, s[6:7] offset:2112
	global_load_dword v118, v187, s[6:7] offset:2176
	global_load_dword v119, v187, s[6:7] offset:2240
	global_load_dword v120, v187, s[6:7] offset:3072
	global_load_dword v121, v187, s[6:7] offset:3136
	global_load_dword v122, v187, s[6:7] offset:3200
	global_load_dword v123, v187, s[6:7] offset:3264
	v_readlane_b32 s9, v252, 41
	v_readlane_b32 s10, v252, 42
	v_readlane_b32 s11, v252, 43
	v_readlane_b32 s12, v252, 44
	v_readlane_b32 s13, v252, 45
	v_readlane_b32 s14, v252, 46
	v_readlane_b32 s15, v252, 47
	v_readlane_b32 s16, v252, 48
	v_readlane_b32 s17, v252, 49
	v_readlane_b32 s20, v252, 52
	v_readlane_b32 s21, v252, 53
	v_readlane_b32 s22, v252, 54
	v_readlane_b32 s23, v252, 55
	v_mul_u32_u24_e32 v176, 0x1010, v172
	v_lshl_add_u32 v180, v173, 4, v176
	v_mul_u32_u24_e32 v181, 0x1010, v174
	v_lshl_add_u32 v181, v172, 9, v181
	v_lshl_add_u32 v181, v175, 4, v181
	v_lshlrev_b32_e32 v182, 10, v172
	v_lshl_add_u32 v182, v173, 2, v182
	v_add_u32_e32 v182, 0x10100, v182
	v_bfe_u32 v177, v38, 4, 1
	v_lshl_add_u32 v177, v172, 1, v177
	v_and_b32_e32 v178, 3, v177
	v_lshrrev_b32_e32 v179, 2, v177
	v_lshl_add_u32 v179, v179, 4, v174
	v_lshlrev_b32_e32 v183, 2, v179
	v_lshl_add_u32 v183, v178, 8, v183
	v_add_u32_e32 v183, 0x10100, v183
	v_readlane_b32 s4, v252, 7
	v_and_b32_e32 v178, 7, v177
	v_lshrrev_b32_e32 v179, 3, v177
	v_lshl_add_u32 v178, v179, 11, v178
	s_nop 1
	v_add_u32_e32 v178, s4, v178
	v_lshlrev_b32_e32 v184, 2, v178
	v_lshl_add_u32 v184, v174, 16, v184
	v_add_u32_e32 v184, 0x33601000, v184
	v_mov_b32_e32 v185, 0
	v_lshl_add_u64 v[184:185], s[86:87], 0, v[184:185]
	v_ashrrev_i32_e32 v0, 6, v38
	v_add_u32_e32 v32, s4, v0
	s_movk_i32 s4, 0x4000
	v_cmp_gt_i32_e32 vcc, s4, v32
	s_waitcnt lgkmcnt(0)
	s_barrier
	s_and_saveexec_b64 s[24:25], vcc
	s_cbranch_execz .LBB0_318
	s_lshl_b32 s4, s26, 10
	s_ashr_i32 s5, s4, 31
	v_readlane_b32 s8, v252, 40
	s_lshl_b64 s[4:5], s[4:5], 2
	v_readlane_b32 s16, v252, 48
	v_readlane_b32 s17, v252, 49
	s_add_u32 s6, s16, s4
	v_readlane_b32 s14, v252, 46
	s_addc_u32 s7, s17, s5
	v_readlane_b32 s15, v252, 47
	v_and_b32_e32 v39, 63, v38
	s_add_u32 s4, s14, s4
	v_lshlrev_b32_e32 v40, 4, v39
	s_addc_u32 s5, s15, s5
	global_load_dwordx4 v[0:3], v40, s[6:7] offset:3072
	global_load_dwordx4 v[4:7], v40, s[4:5] offset:3072
	global_load_dwordx4 v[8:11], v40, s[6:7] offset:2048
	global_load_dwordx4 v[12:15], v40, s[4:5] offset:2048
	global_load_dwordx4 v[16:19], v40, s[6:7] offset:1024
	global_load_dwordx4 v[20:23], v40, s[4:5] offset:1024
	global_load_dwordx4 v[24:27], v40, s[6:7]
	global_load_dwordx4 v[28:31], v40, s[4:5]
	v_ashrrev_i32_e32 v33, 31, v32
	v_readlane_b32 s4, v252, 59
	v_lshlrev_b64 v[34:35], 11, v[32:33]
	v_readlane_b32 s5, v252, 60
	v_lshlrev_b32_e32 v188, 3, v39
	v_and_b32_e32 v39, 64, v211
	v_lshl_add_u64 v[36:37], s[4:5], 0, v[34:35]
	v_lshl_add_u64 v[36:37], v[36:37], 0, v[188:189]
	global_load_dwordx2 v[54:55], v[36:37], off
	global_load_dwordx2 v[52:53], v[36:37], off offset:512
	global_load_dwordx2 v[50:51], v[36:37], off offset:1024
	global_load_dwordx2 v[48:49], v[36:37], off offset:1536
	v_add_u32_e32 v39, 64, v39
	v_xor_b32_e32 v41, 32, v211
	v_cmp_lt_i32_e32 vcc, v41, v39
	v_lshl_add_u64 v[36:37], s[4:5], 0, v[188:189]
	v_readlane_b32 s9, v252, 41
	v_cndmask_b32_e32 v41, v211, v41, vcc
	v_lshlrev_b32_e32 v64, 2, v41
	v_xor_b32_e32 v41, 16, v211
	v_cmp_lt_i32_e32 vcc, v41, v39
	v_readlane_b32 s10, v252, 42
	v_readlane_b32 s11, v252, 43
	v_cndmask_b32_e32 v41, v211, v41, vcc
	v_lshlrev_b32_e32 v65, 2, v41
	v_xor_b32_e32 v41, 8, v211
	v_cmp_lt_i32_e32 vcc, v41, v39
	v_readlane_b32 s12, v252, 44
	v_readlane_b32 s13, v252, 45
	v_cndmask_b32_e32 v41, v211, v41, vcc
	v_lshlrev_b32_e32 v66, 2, v41
	v_xor_b32_e32 v41, 4, v211
	v_cmp_lt_i32_e32 vcc, v41, v39
	v_readlane_b32 s18, v252, 50
	v_readlane_b32 s19, v252, 51
	v_cndmask_b32_e32 v41, v211, v41, vcc
	v_lshlrev_b32_e32 v67, 2, v41
	v_xor_b32_e32 v41, 2, v211
	v_cmp_lt_i32_e32 vcc, v41, v39
	s_mov_b64 s[14:15], 0x33601000
	v_add_u32_e32 v70, 0, v40
	v_cndmask_b32_e32 v41, v211, v41, vcc
	v_lshlrev_b32_e32 v68, 2, v41
	v_xor_b32_e32 v41, 1, v211
	v_cmp_lt_i32_e32 vcc, v41, v39
	v_or_b32_e32 v34, v34, v188
	s_mov_b64 s[18:19], 0
	v_cndmask_b32_e32 v39, v211, v41, vcc
	v_lshlrev_b32_e32 v69, 2, v39
	v_and_b32_e32 v39, 32, v38
	v_cmp_eq_u32_e64 s[4:5], 0, v39
	v_and_b32_e32 v39, 16, v38
	v_cmp_eq_u32_e64 s[6:7], 0, v39
	v_and_b32_e32 v39, 8, v38
	v_cmp_eq_u32_e64 s[8:9], 0, v39
	v_and_b32_e32 v39, 4, v38
	v_cmp_eq_u32_e64 s[10:11], 0, v39
	v_and_b32_e32 v39, 3, v38
	v_lshlrev_b32_e32 v38, 14, v38
	v_cmp_eq_u32_e64 s[12:13], 0, v39
	v_and_b32_e32 v38, 0xf0000, v38
	v_mov_b32_e32 v39, v189
	v_lshl_add_u64 v[38:39], v[32:33], 2, v[38:39]
	v_lshl_add_u64 v[38:39], v[38:39], 0, s[14:15]
	v_readlane_b32 s20, v252, 52
	v_readlane_b32 s21, v252, 53
	v_readlane_b32 s22, v252, 54
	v_readlane_b32 s23, v252, 55
	s_waitcnt vmcnt(3)
; __device__ __forceinline__ float bf_lo(unsigned w) { return __uint_as_float(w << 16); }
; __device__ __forceinline__ float bf_hi(unsigned w) { return __uint_as_float(w & 0xffff0000u); }
; __device__ void phase_ln1_router(const Params& p, int l, LAS unsigned char* lds) {
;     ...
;     u32x2 raw[4];
;     { const int row0 = blockIdx.x * 8 + wv;
;       if (row0 < SEQ) {
; #pragma unroll
;           for (int j = 0; j < 4; ++j) raw[j] = *(const u32x2*)(XP + (size_t)row0 * DM + lane * 4 + 256 * j); } }
;     for (int row = blockIdx.x * 8 + wv; row < SEQ; row += rstride) {
;         f32x4 v[4]; float s = 0.f;
; #pragma unroll
;         for (int j = 0; j < 4; ++j) { const u32x2 w = raw[j]; v[j] = (f32x4){bf_lo(w.x), bf_hi(w.x), bf_lo(w.y), bf_hi(w.y)}; s += (v[j][0] + v[j][1]) + (v[j][2] + v[j][3]); }
;         if (row + rstride < SEQ) {
; #pragma unroll
;             for (int j = 0; j < 4; ++j) raw[j] = *(const u32x2*)(XP + (size_t)(row + rstride) * DM + lane * 4 + 256 * j); }
	v_mov_b64_e32 v[40:41], v[54:55]
	s_waitcnt vmcnt(2)
	v_mov_b64_e32 v[42:43], v[52:53]
	s_waitcnt vmcnt(1)
	v_mov_b64_e32 v[44:45], v[50:51]
	s_waitcnt vmcnt(0)
	v_mov_b64_e32 v[46:47], v[48:49]
	v_mov_b32_e32 v248, v32
	v_ashrrev_i32_e32 v249, 31, v32
	v_lshlrev_b64 v[246:247], 11, v[248:249]
	v_lshl_add_u64 v[246:247], v[36:37], 0, v[246:247]
	v_add_co_u32_e32 v246, vcc, 0x400000, v246
	s_nop 1
	v_addc_co_u32_e32 v247, vcc, 0, v247, vcc
	global_load_dwordx2 v[80:81], v[246:247], off
	global_load_dwordx2 v[82:83], v[246:247], off offset:512
	global_load_dwordx2 v[84:85], v[246:247], off offset:1024
	global_load_dwordx2 v[86:87], v[246:247], off offset:1536
	v_add_co_u32_e32 v246, vcc, 0x400000, v246
	s_nop 1
	v_addc_co_u32_e32 v247, vcc, 0, v247, vcc
	global_load_dwordx2 v[88:89], v[246:247], off
	global_load_dwordx2 v[90:91], v[246:247], off offset:512
	global_load_dwordx2 v[190:191], v[246:247], off offset:1024
	global_load_dwordx2 v[192:193], v[246:247], off offset:1536
	v_add_co_u32_e32 v246, vcc, 0x400000, v246
	s_nop 1
	v_addc_co_u32_e32 v247, vcc, 0, v247, vcc
	global_load_dwordx2 v[194:195], v[246:247], off
	global_load_dwordx2 v[196:197], v[246:247], off offset:512
	global_load_dwordx2 v[198:199], v[246:247], off offset:1024
	global_load_dwordx2 v[200:201], v[246:247], off offset:1536
	v_add_co_u32_e32 v246, vcc, 0x400000, v246
	s_nop 1
	v_addc_co_u32_e32 v247, vcc, 0, v247, vcc
	global_load_dwordx2 v[202:203], v[246:247], off
	global_load_dwordx2 v[204:205], v[246:247], off offset:512
	global_load_dwordx2 v[206:207], v[246:247], off offset:1024
	global_load_dwordx2 v[208:209], v[246:247], off offset:1536
	v_add_co_u32_e32 v246, vcc, 0x400000, v246
	s_nop 1
	v_addc_co_u32_e32 v247, vcc, 0, v247, vcc
	global_load_dwordx2 v[222:223], v[246:247], off
	global_load_dwordx2 v[224:225], v[246:247], off offset:512
	global_load_dwordx2 v[226:227], v[246:247], off offset:1024
	global_load_dwordx2 v[228:229], v[246:247], off offset:1536
	v_add_co_u32_e32 v246, vcc, 0x400000, v246
	s_nop 1
	v_addc_co_u32_e32 v247, vcc, 0, v247, vcc
	global_load_dwordx2 v[230:231], v[246:247], off
	global_load_dwordx2 v[232:233], v[246:247], off offset:512
	global_load_dwordx2 v[234:235], v[246:247], off offset:1024
	global_load_dwordx2 v[236:237], v[246:247], off offset:1536
	v_add_co_u32_e32 v246, vcc, 0x400000, v246
	s_nop 1
	v_addc_co_u32_e32 v247, vcc, 0, v247, vcc
	global_load_dwordx2 v[238:239], v[246:247], off
	global_load_dwordx2 v[240:241], v[246:247], off offset:512
	global_load_dwordx2 v[242:243], v[246:247], off offset:1024
	global_load_dwordx2 v[244:245], v[246:247], off offset:1536
	s_mov_b32 s7, 1
	s_mov_b32 s6, 0
	s_branch .LBB0_314
.LBB0_313:
	s_or_b64 exec, exec, s[20:21]
	s_and_b64 s[14:15], exec, s[14:15]
	s_or_b64 s[18:19], s[14:15], s[18:19]
	v_readlane_b32 s14, v254, 44
	v_readlane_b32 s15, v254, 45
	v_lshl_add_u64 v[38:39], v[38:39], 0, s[14:15]
	v_readlane_b32 s14, v254, 46
	v_readlane_b32 s15, v254, 47
	s_cmp_eq_u32 s7, 1
	s_cbranch_scc1 .Lln1_row1
	s_cmp_eq_u32 s7, 2
	s_cbranch_scc1 .Lln1_row2
	s_cmp_eq_u32 s7, 3
	s_cbranch_scc1 .Lln1_row3
	s_cmp_eq_u32 s7, 4
	s_cbranch_scc1 .Lln1_row4
	s_cmp_eq_u32 s7, 5
	s_cbranch_scc1 .Lln1_row5
	s_cmp_eq_u32 s7, 6
	s_cbranch_scc1 .Lln1_row6
	s_cmp_eq_u32 s7, 7
	s_cbranch_scc1 .Lln1_row7
	s_waitcnt lgkmcnt(0)
	s_branch .Lln1_rowdone
.Lln1_row1:
	s_waitcnt vmcnt(24) lgkmcnt(0)
	v_mov_b64_e32 v[54:55], v[80:81]
	v_mov_b64_e32 v[52:53], v[82:83]
	v_mov_b64_e32 v[50:51], v[84:85]
	v_mov_b64_e32 v[48:49], v[86:87]
	s_branch .Lln1_rowdone
.Lln1_row2:
	s_waitcnt vmcnt(20) lgkmcnt(0)
	v_mov_b64_e32 v[54:55], v[88:89]
	v_mov_b64_e32 v[52:53], v[90:91]
	v_mov_b64_e32 v[50:51], v[190:191]
	v_mov_b64_e32 v[48:49], v[192:193]
	s_branch .Lln1_rowdone
.Lln1_row3:
	s_waitcnt vmcnt(16) lgkmcnt(0)
	v_mov_b64_e32 v[54:55], v[194:195]
	v_mov_b64_e32 v[52:53], v[196:197]
	v_mov_b64_e32 v[50:51], v[198:199]
	v_mov_b64_e32 v[48:49], v[200:201]
	s_branch .Lln1_rowdone
.Lln1_row4:
	s_waitcnt vmcnt(12) lgkmcnt(0)
	v_mov_b64_e32 v[54:55], v[202:203]
	v_mov_b64_e32 v[52:53], v[204:205]
	v_mov_b64_e32 v[50:51], v[206:207]
	v_mov_b64_e32 v[48:49], v[208:209]
	s_branch .Lln1_rowdone
.Lln1_row5:
	s_waitcnt vmcnt(8) lgkmcnt(0)
	v_mov_b64_e32 v[54:55], v[222:223]
	v_mov_b64_e32 v[52:53], v[224:225]
	v_mov_b64_e32 v[50:51], v[226:227]
	v_mov_b64_e32 v[48:49], v[228:229]
	s_branch .Lln1_rowdone
.Lln1_row6:
	s_waitcnt vmcnt(4) lgkmcnt(0)
	v_mov_b64_e32 v[54:55], v[230:231]
	v_mov_b64_e32 v[52:53], v[232:233]
	v_mov_b64_e32 v[50:51], v[234:235]
	v_mov_b64_e32 v[48:49], v[236:237]
	s_branch .Lln1_rowdone
.Lln1_row7:
	s_waitcnt vmcnt(0) lgkmcnt(0)
	v_mov_b64_e32 v[54:55], v[238:239]
	v_mov_b64_e32 v[52:53], v[240:241]
	v_mov_b64_e32 v[50:51], v[242:243]
	v_mov_b64_e32 v[48:49], v[244:245]
.Lln1_rowdone:
	s_add_i32 s7, s7, 1
	v_lshl_add_u64 v[34:35], v[34:35], 0, s[14:15]
	s_andn2_b64 exec, exec, s[18:19]
	s_cbranch_execz .LBB0_318

; #define LAS __attribute__((address_space(3)))
; __device__ __forceinline__ unsigned cvt_pk_bf16(float lo, float hi) { unsigned r; asm("v_cvt_pk_bf16_f32 %0, %1, %2" : "=v"(r) : "v"(lo), "v"(hi)); return r; }
; __device__ __forceinline__ float bf_lo(unsigned w) { return __uint_as_float(w << 16); }
; __device__ __forceinline__ float bf_hi(unsigned w) { return __uint_as_float(w & 0xffff0000u); }
; __device__ void phase_ln1_router(const Params& p, int l, LAS unsigned char* lds) {
;     ...
;         f32x4 v[4]; float s = 0.f;
; #pragma unroll
;         for (int j = 0; j < 4; ++j) { const u32x2 w = raw[j]; v[j] = (f32x4){bf_lo(w.x), bf_hi(w.x), bf_lo(w.y), bf_hi(w.y)}; s += (v[j][0] + v[j][1]) + (v[j][2] + v[j][3]); }
;         if (row + rstride < SEQ) {
; #pragma unroll
;             for (int j = 0; j < 4; ++j) raw[j] = *(const u32x2*)(XP + (size_t)(row + rstride) * DM + lane * 4 + 256 * j); }
;         const float mean = wave_sum(s) * (1.0f / 1024.0f); float q = 0.f;
; #pragma unroll
;         for (int j = 0; j < 4; ++j) { v[j] = v[j] - mean; q += (v[j][0] * v[j][0] + v[j][1] * v[j][1]) + (v[j][2] * v[j][2] + v[j][3] * v[j][3]); }
;         const float rstd = rsqrtf(wave_sum(q) * (1.0f / 1024.0f) + 1e-5f);
; #pragma unroll
;         for (int j = 0; j < 4; ++j) { v[j] = v[j] * rstd * gv[j] + bv[j];
;             u32x2 w; w.x = cvt_pk_bf16(v[j][0], v[j][1]); w.y = cvt_pk_bf16(v[j][2], v[j][3]); *(u32x2*)(XB + (size_t)row * DM + lane * 4 + 256 * j) = w; }
;         float a16[16];
; #pragma unroll
;         for (int e = 0; e < 16; ++e) { float a = 0.f;
; #pragma unroll
;             for (int j = 0; j < 4; ++j) { const f32x4 w = *(const LAS f32x4*)(rw_s + e * RWP + lane * 4 + 256 * j); a += v[j][0] * w[0] + v[j][1] * w[1] + v[j][2] * w[2] + v[j][3] * w[3]; }
;             a16[e] = a; }
.LBB0_316:
	s_or_b64 exec, exec, s[20:21]
	v_lshlrev_b32_e32 v56, 16, v54
	v_and_b32_e32 v57, 0xffff0000, v54
	v_lshlrev_b32_e32 v54, 16, v55
	v_and_b32_e32 v55, 0xffff0000, v55
	v_add_f32_e32 v33, v56, v57
	v_add_f32_e32 v58, v54, v55
	v_add_f32_e32 v33, v33, v58
	v_lshlrev_b32_e32 v58, 16, v52
	v_and_b32_e32 v59, 0xffff0000, v52
	v_lshlrev_b32_e32 v52, 16, v53
	v_and_b32_e32 v53, 0xffff0000, v53
	v_add_f32_e32 v60, v58, v59
	v_add_f32_e32 v61, v52, v53
	v_add_f32_e32 v33, 0, v33
	v_add_f32_e32 v60, v60, v61
	v_lshlrev_b32_e32 v72, 16, v50
	v_and_b32_e32 v73, 0xffff0000, v50
	v_lshlrev_b32_e32 v50, 16, v51
	v_and_b32_e32 v51, 0xffff0000, v51
	v_add_f32_e32 v33, v33, v60
	v_add_f32_e32 v60, v72, v73
	v_add_f32_e32 v61, v50, v51
	v_add_f32_e32 v60, v60, v61
	v_lshlrev_b32_e32 v74, 16, v48
	v_and_b32_e32 v75, 0xffff0000, v48
	v_lshlrev_b32_e32 v48, 16, v49
	v_and_b32_e32 v49, 0xffff0000, v49
	v_add_f32_e32 v33, v33, v60
	v_add_f32_e32 v60, v74, v75
	v_add_f32_e32 v61, v48, v49
	v_add_f32_e32 v60, v60, v61
	v_add_f32_e32 v33, v33, v60
	v_mov_b32_e32 v60, v33
	s_mov_b32 s20, 0x1a601000
	s_waitcnt lgkmcnt(0)
	s_nop 1
	v_permlane32_swap_b32_e32 v60, v33
	v_add_f32_e32 v33, v33, v60
	v_mov_b32_e32 v60, v33
	s_waitcnt lgkmcnt(0)
	s_nop 1
	v_permlane16_swap_b32_e32 v60, v33
	v_add_f32_e32 v33, v33, v60
	s_waitcnt lgkmcnt(0)
	s_nop 1
	v_add_f32_dpp v33, v33, v33 row_ror:8 row_mask:0xf bank_mask:0xf
	s_waitcnt lgkmcnt(0)
	s_nop 1
	v_add_f32_dpp v33, v33, v33 row_ror:4 row_mask:0xf bank_mask:0xf
	s_waitcnt lgkmcnt(0)
	s_nop 1
	v_add_f32_dpp v33, v33, v33 quad_perm:[2,3,0,1] row_mask:0xf bank_mask:0xf
	s_waitcnt lgkmcnt(0)
	s_nop 1
	v_add_f32_dpp v33, v33, v33 quad_perm:[1,0,3,2] row_mask:0xf bank_mask:0xf
	v_fmac_f32_e32 v57, 0xba800000, v33
	v_fmac_f32_e32 v56, 0xba800000, v33
	v_fmac_f32_e32 v55, 0xba800000, v33
	v_fmac_f32_e32 v54, 0xba800000, v33
	v_pk_mul_f32 v[60:61], v[54:55], v[54:55]
	v_pk_mul_f32 v[62:63], v[56:57], v[56:57]
	v_fmac_f32_e32 v59, 0xba800000, v33
	v_pk_mov_b32 v[76:77], v[62:63], v[60:61] op_sel:[1,0]
	v_mov_b32_e32 v63, v61
	v_pk_add_f32 v[60:61], v[76:77], v[62:63]
	v_fmac_f32_e32 v58, 0xba800000, v33
	v_fmac_f32_e32 v53, 0xba800000, v33
	v_fmac_f32_e32 v52, 0xba800000, v33
	v_pk_add_f32 v[60:61], v[60:61], v[60:61] op_sel_hi:[0,1]
	v_pk_mul_f32 v[62:63], v[52:53], v[52:53]
	v_pk_mul_f32 v[76:77], v[58:59], v[58:59]
	v_fmac_f32_e32 v72, 0xba800000, v33
	v_pk_mov_b32 v[78:79], v[76:77], v[62:63] op_sel:[1,0]
	v_mov_b32_e32 v77, v63
	v_fmac_f32_e32 v73, 0xba800000, v33
	v_fmac_f32_e32 v50, 0xba800000, v33
	v_mul_f32_e32 v60, v72, v72
	v_pk_add_f32 v[62:63], v[78:79], v[76:77]
	v_fmac_f32_e32 v51, 0xba800000, v33
	v_pk_fma_f32 v[76:77], v[72:73], v[72:73], v[60:61] op_sel_hi:[1,1,0]
	v_mul_f32_e32 v60, v50, v50
	v_pk_add_f32 v[62:63], v[62:63], v[62:63] op_sel_hi:[0,1]
	v_pk_fma_f32 v[78:79], v[50:51], v[50:51], v[60:61] op_sel_hi:[1,1,0]
	v_fmac_f32_e32 v49, 0xba800000, v33
	v_fmac_f32_e32 v48, 0xba800000, v33
	v_fmac_f32_e32 v75, 0xba800000, v33
	v_fmac_f32_e32 v74, 0xba800000, v33
	v_mul_f32_e32 v76, v74, v74
	v_mul_f32_e32 v78, v75, v75
	v_mul_f32_e32 v60, v48, v48
	v_mul_f32_e32 v62, v49, v49
	v_pk_add_f32 v[76:77], v[76:77], v[78:79]
	v_pk_add_f32 v[60:61], v[60:61], v[62:63]
	v_lshl_add_u64 v[78:79], s[86:87], 0, v[34:35]
	v_pk_add_f32 v[60:61], v[76:77], v[60:61]
	s_nop 0
	v_add_f32_e32 v33, v60, v61
	v_mov_b32_e32 v60, v33
	s_waitcnt lgkmcnt(0)
	s_nop 1
	v_permlane32_swap_b32_e32 v60, v33
	v_add_f32_e32 v33, v33, v60
	v_mov_b32_e32 v60, v33
	s_waitcnt lgkmcnt(0)
	s_nop 1
	v_permlane16_swap_b32_e32 v60, v33
	v_add_f32_e32 v33, v33, v60
	s_waitcnt lgkmcnt(0)
	s_nop 1
	v_add_f32_dpp v33, v33, v33 row_ror:8 row_mask:0xf bank_mask:0xf
	s_waitcnt lgkmcnt(0)
	s_nop 1
	v_add_f32_dpp v33, v33, v33 row_ror:4 row_mask:0xf bank_mask:0xf
	s_waitcnt lgkmcnt(0)
	s_nop 1
	v_add_f32_dpp v33, v33, v33 quad_perm:[2,3,0,1] row_mask:0xf bank_mask:0xf
	s_waitcnt lgkmcnt(0)
	s_nop 1
	v_add_f32_dpp v33, v33, v33 quad_perm:[1,0,3,2] row_mask:0xf bank_mask:0xf
	v_mov_b32_e32 v60, 0x3727c5ac
	v_fmamk_f32 v33, v33, 0x3a800000, v60
	v_cmp_gt_f32_e32 vcc, s1, v33
	v_mul_f32_e32 v60, 0x4b800000, v33
	s_nop 0
	v_cndmask_b32_e32 v33, v33, v60, vcc
	v_rsq_f32_e32 v33, v33
	s_nop 0
	v_mul_f32_e32 v60, 0x45800000, v33
	v_cndmask_b32_e32 v76, v33, v60, vcc
	v_pk_mul_f32 v[56:57], v[56:57], v[76:77] op_sel_hi:[1,0]
	v_pk_mul_f32 v[54:55], v[54:55], v[76:77] op_sel_hi:[1,0]
	v_add_co_u32_e32 v78, vcc, s20, v78
	v_pk_fma_f32 v[60:61], v[30:31], v[54:55], v[26:27]
	v_pk_fma_f32 v[62:63], v[28:29], v[56:57], v[24:25]
	v_cvt_pk_bf16_f32 v55, v60, v61
	v_addc_co_u32_e32 v79, vcc, 0, v79, vcc
	v_cvt_pk_bf16_f32 v54, v62, v63
	global_store_dwordx2 v[78:79], v[54:55], off
	v_pk_mul_f32 v[54:55], v[58:59], v[76:77] op_sel_hi:[1,0]
	v_pk_mul_f32 v[52:53], v[52:53], v[76:77] op_sel_hi:[1,0]
	v_pk_fma_f32 v[54:55], v[20:21], v[54:55], v[16:17]
	v_pk_fma_f32 v[52:53], v[22:23], v[52:53], v[18:19]
	v_cvt_pk_bf16_f32 v56, v54, v55
	v_pk_mul_f32 v[58:59], v[72:73], v[76:77] op_sel_hi:[1,0]
	v_cvt_pk_bf16_f32 v57, v52, v53
	v_pk_mul_f32 v[50:51], v[50:51], v[76:77] op_sel_hi:[1,0]
	global_store_dwordx2 v[78:79], v[56:57], off offset:512
	v_pk_fma_f32 v[56:57], v[14:15], v[50:51], v[10:11]
	v_pk_fma_f32 v[58:59], v[12:13], v[58:59], v[8:9]
	v_cvt_pk_bf16_f32 v51, v56, v57
	v_pk_mul_f32 v[48:49], v[48:49], v[76:77] op_sel_hi:[1,0]
	v_cvt_pk_bf16_f32 v50, v58, v59
	global_store_dwordx2 v[78:79], v[50:51], off offset:1024
	v_pk_mul_f32 v[50:51], v[74:75], v[76:77] op_sel_hi:[1,0]
	v_pk_fma_f32 v[48:49], v[6:7], v[48:49], v[2:3]
	v_pk_fma_f32 v[50:51], v[4:5], v[50:51], v[0:1]
	v_cvt_pk_bf16_f32 v73, v48, v49
	s_mov_b32 s20, 0x3fb8aa3b
	v_cvt_pk_bf16_f32 v72, v50, v51
	global_store_dwordx2 v[78:79], v[72:73], off offset:1536
	v_add_u32_e32 v186, s6, v180
	ds_write_b64 v186, v[62:63]
	ds_write_b64 v186, v[60:61] offset:8
	ds_write_b64 v186, v[54:55] offset:1024
	ds_write_b64 v186, v[52:53] offset:1032
	ds_write_b64 v186, v[58:59] offset:2048
	ds_write_b64 v186, v[56:57] offset:2056
	ds_write_b64 v186, v[50:51] offset:3072
	ds_write_b64 v186, v[48:49] offset:3080
	s_cmp_lg_u32 s6, 0
	s_cselect_b32 s6, 0, 0x8080
	s_cbranch_scc0 .Lln1_skip
; #define LAS __attribute__((address_space(3)))
; __device__ void phase_ln1_router(const Params& p, int l, LAS unsigned char* lds) {
;     ...
;         float a16[16];
; #pragma unroll
;         for (int e = 0; e < 16; ++e) { float a = 0.f;
; #pragma unroll
;             for (int j = 0; j < 4; ++j) { const f32x4 w = *(const LAS f32x4*)(rw_s + e * RWP + lane * 4 + 256 * j); a += v[j][0] * w[0] + v[j][1] * w[1] + v[j][2] * w[2] + v[j][3] * w[3]; }
;             a16[e] = a; }
;         float b8[8], c4[4], d2[2];
;         { const bool hi = (lane & 32) != 0;
; #pragma unroll
;           for (int i = 0; i < 8; ++i) { const float keep = hi ? a16[8 + i] : a16[i], send = hi ? a16[i] : a16[8 + i]; b8[i] = keep + __shfl_xor(send, 32); } }
;         { const bool hi = (lane & 16) != 0;
; #pragma unroll
;           for (int i = 0; i < 4; ++i) { const float keep = hi ? b8[4 + i] : b8[i], send = hi ? b8[i] : b8[4 + i]; c4[i] = keep + __shfl_xor(send, 16); } }
;         { const bool hi = (lane & 8) != 0;
; #pragma unroll
;           for (int i = 0; i < 2; ++i) { const float keep = hi ? c4[2 + i] : c4[i], send = hi ? c4[i] : c4[2 + i]; d2[i] = keep + __shfl_xor(send, 8); } }
;         float lgt; { const bool hi = (lane & 4) != 0; const float keep = hi ? d2[1] : d2[0], send = hi ? d2[0] : d2[1]; lgt = keep + __shfl_xor(send, 4); }
;         lgt += __shfl_xor(lgt, 2); lgt += __shfl_xor(lgt, 1);
;         float mx = lgt;
;         mx = fmaxf(mx, __shfl_xor(mx, 4)); mx = fmaxf(mx, __shfl_xor(mx, 8)); mx = fmaxf(mx, __shfl_xor(mx, 16)); mx = fmaxf(mx, __shfl_xor(mx, 32));
;         const float ex = expf(lgt - mx);
;         float den = ex; den += __shfl_xor(den, 4); den += __shfl_xor(den, 8); den += __shfl_xor(den, 16); den += __shfl_xor(den, 32);
;         const int eidx = ((lane >> 5) & 1) * 8 + ((lane >> 4) & 1) * 4 + ((lane >> 3) & 1) * 2 + ((lane >> 2) & 1);
;         if ((lane & 3) == 0) AFF[(size_t)eidx * SEQ + row] = ex / den;
	s_waitcnt lgkmcnt(0)
	s_barrier
	ds_read_b128 v[124:127], v181 offset:0
	ds_read_b128 v[128:131], v181 offset:64
	ds_read_b128 v[132:135], v181 offset:128
	ds_read_b128 v[136:139], v181 offset:192
	ds_read_b128 v[140:143], v181 offset:256
	ds_read_b128 v[144:147], v181 offset:320
	ds_read_b128 v[148:151], v181 offset:384
	ds_read_b128 v[152:155], v181 offset:448
	s_waitcnt lgkmcnt(7)
	v_mfma_f32_16x16x4_f32 v[156:159], v124, v92, 0
	v_mfma_f32_16x16x4_f32 v[160:163], v125, v93, 0
	v_mfma_f32_16x16x4_f32 v[156:159], v126, v94, v[156:159]
	v_mfma_f32_16x16x4_f32 v[160:163], v127, v95, v[160:163]
	s_waitcnt lgkmcnt(6)
	v_mfma_f32_16x16x4_f32 v[156:159], v128, v96, v[156:159]
	v_mfma_f32_16x16x4_f32 v[160:163], v129, v97, v[160:163]
	v_mfma_f32_16x16x4_f32 v[156:159], v130, v98, v[156:159]
	v_mfma_f32_16x16x4_f32 v[160:163], v131, v99, v[160:163]
	s_waitcnt lgkmcnt(5)
	v_mfma_f32_16x16x4_f32 v[156:159], v132, v100, v[156:159]
	v_mfma_f32_16x16x4_f32 v[160:163], v133, v101, v[160:163]
	v_mfma_f32_16x16x4_f32 v[156:159], v134, v102, v[156:159]
	v_mfma_f32_16x16x4_f32 v[160:163], v135, v103, v[160:163]
	s_waitcnt lgkmcnt(4)
	v_mfma_f32_16x16x4_f32 v[156:159], v136, v104, v[156:159]
	v_mfma_f32_16x16x4_f32 v[160:163], v137, v105, v[160:163]
	v_mfma_f32_16x16x4_f32 v[156:159], v138, v106, v[156:159]
	v_mfma_f32_16x16x4_f32 v[160:163], v139, v107, v[160:163]
	s_waitcnt lgkmcnt(3)
	v_mfma_f32_16x16x4_f32 v[156:159], v140, v108, v[156:159]
	v_mfma_f32_16x16x4_f32 v[160:163], v141, v109, v[160:163]
	v_mfma_f32_16x16x4_f32 v[156:159], v142, v110, v[156:159]
	v_mfma_f32_16x16x4_f32 v[160:163], v143, v111, v[160:163]
	s_waitcnt lgkmcnt(2)
	v_mfma_f32_16x16x4_f32 v[156:159], v144, v112, v[156:159]
	v_mfma_f32_16x16x4_f32 v[160:163], v145, v113, v[160:163]
	v_mfma_f32_16x16x4_f32 v[156:159], v146, v114, v[156:159]
	v_mfma_f32_16x16x4_f32 v[160:163], v147, v115, v[160:163]
	s_waitcnt lgkmcnt(1)
	v_mfma_f32_16x16x4_f32 v[156:159], v148, v116, v[156:159]
	v_mfma_f32_16x16x4_f32 v[160:163], v149, v117, v[160:163]
	v_mfma_f32_16x16x4_f32 v[156:159], v150, v118, v[156:159]
	v_mfma_f32_16x16x4_f32 v[160:163], v151, v119, v[160:163]
	s_waitcnt lgkmcnt(0)
	v_mfma_f32_16x16x4_f32 v[156:159], v152, v120, v[156:159]
	v_mfma_f32_16x16x4_f32 v[160:163], v153, v121, v[160:163]
	v_mfma_f32_16x16x4_f32 v[156:159], v154, v122, v[156:159]
	v_mfma_f32_16x16x4_f32 v[160:163], v155, v123, v[160:163]
	s_nop 15
	v_add_f32_e32 v156, v156, v160
	v_add_f32_e32 v157, v157, v161
	v_add_f32_e32 v158, v158, v162
	v_add_f32_e32 v159, v159, v163
	ds_write_b32 v182, v156
	ds_write_b32 v182, v157 offset:256
	ds_write_b32 v182, v158 offset:512
	ds_write_b32 v182, v159 offset:768
	s_waitcnt lgkmcnt(0)
	s_barrier
	ds_read_b32 v164, v183
	ds_read_b32 v165, v183 offset:1024
	ds_read_b32 v166, v183 offset:2048
	ds_read_b32 v167, v183 offset:3072
	ds_read_b32 v168, v183 offset:4096
	ds_read_b32 v169, v183 offset:5120
	ds_read_b32 v170, v183 offset:6144
	ds_read_b32 v171, v183 offset:7168
	s_waitcnt lgkmcnt(0)
	v_add_f32_e32 v172, v164, v165
	v_add_f32_e32 v172, v172, v166
	v_add_f32_e32 v172, v172, v167
	v_add_f32_e32 v172, v172, v168
	v_add_f32_e32 v172, v172, v169
	v_add_f32_e32 v172, v172, v170
	v_add_f32_e32 v172, v172, v171
	v_mov_b32_e32 v173, v172
	s_nop 1
	v_max_f32_dpp v173, v173, v173 row_ror:8 row_mask:0xf bank_mask:0xf
	s_nop 1
	v_max_f32_dpp v173, v173, v173 row_ror:4 row_mask:0xf bank_mask:0xf
	s_nop 1
	v_max_f32_dpp v173, v173, v173 quad_perm:[2,3,0,1] row_mask:0xf bank_mask:0xf
	s_nop 1
	v_max_f32_dpp v173, v173, v173 quad_perm:[1,0,3,2] row_mask:0xf bank_mask:0xf
	v_sub_f32_e32 v172, v172, v173
	s_mov_b32 s20, 0x3fb8aa3b
	v_mul_f32_e32 v173, 0x3fb8aa3b, v172
	v_fma_f32 v174, v172, s20, -v173
	v_rndne_f32_e32 v175, v173
	v_fmac_f32_e32 v174, 0x32a5705f, v172
	v_sub_f32_e32 v173, v173, v175
	v_add_f32_e32 v173, v173, v174
	v_exp_f32_e32 v173, v173
	v_cvt_i32_f32_e32 v174, v175
	s_mov_b32 s20, 0xc2ce8ed0
	v_cmp_ngt_f32_e32 vcc, s20, v172
	s_mov_b32 s20, 0x42b17218
	v_ldexp_f32 v173, v173, v174
	v_cndmask_b32_e32 v173, 0, v173, vcc
	v_cmp_nlt_f32_e32 vcc, s20, v172
	v_mov_b32_e32 v172, 0x7f800000
	s_nop 0
	v_cndmask_b32_e32 v172, v172, v173, vcc
	v_mov_b32_e32 v173, v172
	s_nop 1
	v_add_f32_dpp v173, v173, v173 row_ror:8 row_mask:0xf bank_mask:0xf
	s_nop 1
	v_add_f32_dpp v173, v173, v173 row_ror:4 row_mask:0xf bank_mask:0xf
	s_nop 1
	v_add_f32_dpp v173, v173, v173 quad_perm:[2,3,0,1] row_mask:0xf bank_mask:0xf
	s_nop 1
	v_add_f32_dpp v173, v173, v173 quad_perm:[1,0,3,2] row_mask:0xf bank_mask:0xf
	v_div_scale_f32 v174, s[22:23], v173, v173, v172
	v_rcp_f32_e32 v175, v174
	v_div_scale_f32 v176, vcc, v172, v173, v172
	v_fma_f32 v177, -v174, v175, 1.0
	v_fmac_f32_e32 v175, v177, v175
	v_mul_f32_e32 v177, v176, v175
	v_fma_f32 v178, -v174, v177, v176
	v_fmac_f32_e32 v177, v178, v175
	v_fma_f32 v174, -v174, v177, v176
	v_div_fmas_f32 v174, v174, v175, v177
	v_div_fixup_f32 v172, v174, v173, v172
	s_mov_b32 s8, -1
	s_mov_b32 s9, 0
	s_mov_b64 exec, s[8:9]
	global_store_dword v[184:185], v172, off
	s_mov_b64 exec, -1
	v_add_co_u32_e32 v184, vcc, 0x4000, v184
	s_nop 1
	v_addc_co_u32_e32 v185, vcc, 0, v185, vcc
.Lln1_skip:
	s_mov_b64 s[20:21], exec
	s_branch .LBB0_313
